# v102 plus P0 row sum-of-squares reduction: ds_bpermute butterfly replaced by DPP moves and permlane16/32 swaps (same pairings, bit-identical)
# baseline (speedup 1.0000x reference)
.LBB0_68:
	s_nop 0
	v_and_b32_e32 v130, 64, v192
	v_add_u32_e32 v130, 64, v130
	v_xor_b32_e32 v131, 1, v192
	v_cmp_lt_i32_e32 vcc, v131, v130
	s_waitcnt vmcnt(1)
	v_mul_f32_e32 v133, v129, v129
	v_fmac_f32_e32 v133, v128, v128
	v_cndmask_b32_e32 v131, v192, v131, vcc
	v_lshlrev_b32_e32 v132, 2, v131
	v_mul_f32_e32 v131, v127, v127
	v_fmac_f32_e32 v131, v126, v126
	v_add_f32_e32 v131, v131, v133
	v_mul_f32_e32 v133, v123, v123
	v_mul_f32_e32 v134, v125, v125
	v_fmac_f32_e32 v133, v122, v122
	v_fmac_f32_e32 v134, v124, v124
	v_add_f32_e32 v133, v133, v134
	v_add_f32_e32 v131, v131, v133
	v_mul_f32_e32 v133, v115, v115
	v_mul_f32_e32 v134, v117, v117
	v_fmac_f32_e32 v133, v114, v114
	v_fmac_f32_e32 v134, v116, v116
	v_add_f32_e32 v133, v133, v134
	v_add_f32_e32 v131, v131, v133
	v_mul_f32_e32 v133, v119, v119
	v_mul_f32_e32 v134, v121, v121
	v_fmac_f32_e32 v133, v118, v118
	v_fmac_f32_e32 v134, v120, v120
	v_add_f32_e32 v133, v133, v134
	v_add_f32_e32 v131, v131, v133
	s_nop 1
	v_mov_b32_dpp v134, v131 quad_perm:[1,0,3,2] row_mask:0xf bank_mask:0xf bound_ctrl:1
	v_xor_b32_e32 v133, 2, v192
	v_cmp_lt_i32_e32 vcc, v133, v130
	s_waitcnt lgkmcnt(0)
	v_add_f32_e32 v131, v131, v134
	v_cndmask_b32_e32 v133, v192, v133, vcc
	v_lshlrev_b32_e32 v133, 2, v133
	s_nop 1
	v_mov_b32_dpp v135, v131 quad_perm:[2,3,0,1] row_mask:0xf bank_mask:0xf bound_ctrl:1
	v_xor_b32_e32 v134, 4, v192
	v_cmp_lt_i32_e32 vcc, v134, v130
	s_waitcnt lgkmcnt(0)
	v_add_f32_e32 v131, v131, v135
	v_cndmask_b32_e32 v134, v192, v134, vcc
	v_lshlrev_b32_e32 v134, 2, v134
	s_nop 1
	v_mov_b32_dpp v136, v131 row_half_mirror row_mask:0xf bank_mask:0xf bound_ctrl:1
	v_xor_b32_e32 v135, 8, v192
	v_cmp_lt_i32_e32 vcc, v135, v130
	s_waitcnt lgkmcnt(0)
	v_add_f32_e32 v131, v131, v136
	v_cndmask_b32_e32 v135, v192, v135, vcc
	v_lshlrev_b32_e32 v135, 2, v135
	s_nop 1
	v_mov_b32_dpp v137, v131 row_mirror row_mask:0xf bank_mask:0xf bound_ctrl:1
	v_xor_b32_e32 v136, 16, v192
	v_cmp_lt_i32_e32 vcc, v136, v130
	s_waitcnt lgkmcnt(0)
	v_add_f32_e32 v131, v131, v137
	v_cndmask_b32_e32 v136, v192, v136, vcc
	v_lshlrev_b32_e32 v136, 2, v136
	v_mov_b32_e32 v138, v131
	v_mov_b32_e32 v207, v131
	s_nop 1
	v_permlane16_swap_b32_e32 v207, v138
	v_xor_b32_e32 v137, 32, v192
	v_cmp_lt_i32_e32 vcc, v137, v130
	s_nop 1
	v_cndmask_b32_e32 v130, v192, v137, vcc
	v_lshlrev_b32_e32 v137, 2, v130
	s_waitcnt lgkmcnt(0)
	v_add_f32_e32 v130, v207, v138
	v_mov_b32_e32 v131, v130
	v_mov_b32_e32 v207, v130
	s_nop 1
	v_permlane32_swap_b32_e32 v207, v131
	s_and_saveexec_b64 s[26:27], s[4:5]
	s_cbranch_execz .LBB0_70
	s_waitcnt lgkmcnt(0)
	v_add_f32_e32 v130, v207, v131
	v_fmamk_f32 v130, v130, 0x3a800000, v193
	v_mul_f32_e32 v131, 0x4f800000, v130
	v_cmp_gt_f32_e32 vcc, s53, v130
	s_nop 1
	v_cndmask_b32_e32 v130, v130, v131, vcc
	v_sqrt_f32_e32 v131, v130
	s_nop 0
	v_add_u32_e32 v138, -1, v131
	v_fma_f32 v140, -v138, v131, v130
	v_add_u32_e32 v139, 1, v131
	v_cmp_ge_f32_e64 s[6:7], 0, v140
	s_nop 1
	v_cndmask_b32_e64 v138, v131, v138, s[6:7]
	v_fma_f32 v131, -v139, v131, v130
	v_cmp_lt_f32_e64 s[6:7], 0, v131
	s_nop 1
	v_cndmask_b32_e64 v131, v138, v139, s[6:7]
	v_mul_f32_e32 v138, 0x37800000, v131
	v_cndmask_b32_e32 v131, v131, v138, vcc
	v_cmp_class_f32_e32 vcc, v130, v194
	s_nop 1
	v_cndmask_b32_e32 v130, v131, v130, vcc
	v_div_scale_f32 v131, s[6:7], v130, v130, 1.0
	v_rcp_f32_e32 v138, v131
	s_add_u32 s6, s38, s18
	s_addc_u32 s7, s39, s19
	v_fma_f32 v139, -v131, v138, 1.0
	v_fmac_f32_e32 v138, v139, v138
	v_div_scale_f32 v139, vcc, 1.0, v130, 1.0
	v_mul_f32_e32 v140, v139, v138
	v_fma_f32 v141, -v131, v140, v139
	v_fmac_f32_e32 v140, v141, v138
	v_fma_f32 v131, -v131, v140, v139
	v_div_fmas_f32 v131, v131, v138, v140
	v_div_fixup_f32 v130, v131, v130, 1.0
	global_store_dword v195, v130, s[6:7]
.LBB0_70:
	s_or_b64 exec, exec, s[26:27]
	v_mul_f32_e32 v130, v111, v111
	s_waitcnt lgkmcnt(0)
	v_mul_f32_e32 v131, v113, v113
	v_fmac_f32_e32 v130, v110, v110
	v_fmac_f32_e32 v131, v112, v112
	v_add_f32_e32 v130, v130, v131
	v_mul_f32_e32 v131, v107, v107
	v_mul_f32_e32 v138, v109, v109
	v_fmac_f32_e32 v131, v106, v106
	v_fmac_f32_e32 v138, v108, v108
	v_add_f32_e32 v131, v131, v138
	v_add_f32_e32 v130, v130, v131
	v_mul_f32_e32 v131, v99, v99
	v_mul_f32_e32 v138, v101, v101
	v_fmac_f32_e32 v131, v98, v98
	v_fmac_f32_e32 v138, v100, v100
	v_add_f32_e32 v131, v131, v138
	v_add_f32_e32 v130, v130, v131
	v_mul_f32_e32 v131, v103, v103
	v_mul_f32_e32 v138, v105, v105
	v_fmac_f32_e32 v131, v102, v102
	v_fmac_f32_e32 v138, v104, v104
	v_add_f32_e32 v131, v131, v138
	v_add_f32_e32 v130, v130, v131
	s_nop 1
	v_mov_b32_dpp v131, v130 quad_perm:[1,0,3,2] row_mask:0xf bank_mask:0xf bound_ctrl:1
	v_cvt_pk_bf16_f32 v126, v126, v127
	v_cvt_pk_bf16_f32 v127, v128, v129
	s_waitcnt lgkmcnt(0)
	v_add_f32_e32 v138, v130, v131
	s_nop 1
	v_mov_b32_dpp v139, v138 quad_perm:[2,3,0,1] row_mask:0xf bank_mask:0xf bound_ctrl:1
	v_lshl_add_u64 v[130:131], s[38:39], 0, v[176:177]
	v_add_co_u32_e32 v128, vcc, 0x4000000, v130
	s_waitcnt lgkmcnt(0)
	v_add_f32_e32 v138, v138, v139
	s_nop 1
	v_mov_b32_dpp v139, v138 row_half_mirror row_mask:0xf bank_mask:0xf bound_ctrl:1
	v_addc_co_u32_e32 v129, vcc, 0, v131, vcc
	global_store_dwordx2 v[128:129], v[126:127], off
	v_cvt_pk_bf16_f32 v122, v122, v123
	s_waitcnt lgkmcnt(0)
	v_add_f32_e32 v138, v138, v139
	s_nop 1
	v_mov_b32_dpp v139, v138 row_mirror row_mask:0xf bank_mask:0xf bound_ctrl:1
	v_cvt_pk_bf16_f32 v123, v124, v125
	global_store_dwordx2 v[128:129], v[122:123], off offset:512
	v_cvt_pk_bf16_f32 v122, v114, v115
	v_cvt_pk_bf16_f32 v123, v116, v117
	s_waitcnt lgkmcnt(0)
	v_add_f32_e32 v126, v138, v139
	v_mov_b32_e32 v127, v126
	v_mov_b32_e32 v207, v126
	s_nop 1
	v_permlane16_swap_b32_e32 v207, v127
	global_store_dwordx2 v[128:129], v[122:123], off offset:1024
	v_cvt_pk_bf16_f32 v116, v118, v119
	v_cvt_pk_bf16_f32 v117, v120, v121
	global_store_dwordx2 v[128:129], v[116:117], off offset:1536
	s_waitcnt lgkmcnt(0)
	v_add_f32_e32 v114, v207, v127
	v_mov_b32_e32 v115, v114
	v_mov_b32_e32 v207, v114
	s_nop 1
	v_permlane32_swap_b32_e32 v207, v115
	s_and_saveexec_b64 s[26:27], s[4:5]
	s_cbranch_execz .LBB0_72
	s_waitcnt lgkmcnt(0)
	v_add_f32_e32 v114, v207, v115
	v_fmamk_f32 v114, v114, 0x3a800000, v193
	v_mul_f32_e32 v115, 0x4f800000, v114
	v_cmp_gt_f32_e32 vcc, s53, v114
	s_nop 1
	v_cndmask_b32_e32 v114, v114, v115, vcc
	v_sqrt_f32_e32 v115, v114
	s_nop 0
	v_add_u32_e32 v116, -1, v115
	v_fma_f32 v118, -v116, v115, v114
	v_add_u32_e32 v117, 1, v115
	v_cmp_ge_f32_e64 s[6:7], 0, v118
	s_nop 1
	v_cndmask_b32_e64 v116, v115, v116, s[6:7]
	v_fma_f32 v115, -v117, v115, v114
	v_cmp_lt_f32_e64 s[6:7], 0, v115
	s_nop 1
	v_cndmask_b32_e64 v115, v116, v117, s[6:7]
	v_mul_f32_e32 v116, 0x37800000, v115
	v_cndmask_b32_e32 v115, v115, v116, vcc
	v_cmp_class_f32_e32 vcc, v114, v194
	s_nop 1
	v_cndmask_b32_e32 v114, v115, v114, vcc
	v_div_scale_f32 v115, s[6:7], v114, v114, 1.0
	v_rcp_f32_e32 v116, v115
	s_add_u32 s6, s38, s18
	s_addc_u32 s7, s39, s19
	v_fma_f32 v117, -v115, v116, 1.0
	v_fmac_f32_e32 v116, v117, v116
	v_div_scale_f32 v117, vcc, 1.0, v114, 1.0
	v_mul_f32_e32 v118, v117, v116
	v_fma_f32 v119, -v115, v118, v117
	v_fmac_f32_e32 v118, v119, v116
	v_fma_f32 v115, -v115, v118, v117
	v_div_fmas_f32 v115, v115, v116, v118
	v_div_fixup_f32 v114, v115, v114, 1.0
	global_store_dword v195, v114, s[6:7] offset:4
.LBB0_72:
	s_or_b64 exec, exec, s[26:27]
	v_mul_f32_e32 v114, v91, v91
	s_waitcnt lgkmcnt(0)
	v_mul_f32_e32 v115, v93, v93
	v_fmac_f32_e32 v114, v90, v90
	v_fmac_f32_e32 v115, v92, v92
	v_add_f32_e32 v114, v114, v115
	v_mul_f32_e32 v115, v87, v87
	v_mul_f32_e32 v116, v89, v89
	v_fmac_f32_e32 v115, v86, v86
	v_fmac_f32_e32 v116, v88, v88
	v_add_f32_e32 v115, v115, v116
	v_add_f32_e32 v114, v114, v115
	v_mul_f32_e32 v115, v83, v83
	v_mul_f32_e32 v116, v85, v85
	v_fmac_f32_e32 v115, v82, v82
	v_fmac_f32_e32 v116, v84, v84
	v_add_f32_e32 v115, v115, v116
	v_add_f32_e32 v114, v114, v115
	v_mul_f32_e32 v115, v95, v95
	v_mul_f32_e32 v116, v97, v97
	v_fmac_f32_e32 v115, v94, v94
	v_fmac_f32_e32 v116, v96, v96
	v_add_f32_e32 v115, v115, v116
	v_add_f32_e32 v114, v114, v115
	s_nop 1
	v_mov_b32_dpp v115, v114 quad_perm:[1,0,3,2] row_mask:0xf bank_mask:0xf bound_ctrl:1
	v_cvt_pk_bf16_f32 v110, v110, v111
	v_cvt_pk_bf16_f32 v111, v112, v113
	v_add_co_u32_e32 v112, vcc, 0x4000000, v130
	s_waitcnt lgkmcnt(0)
	v_add_f32_e32 v114, v114, v115
	s_nop 1
	v_mov_b32_dpp v115, v114 quad_perm:[2,3,0,1] row_mask:0xf bank_mask:0xf bound_ctrl:1
	v_addc_co_u32_e32 v113, vcc, 0, v131, vcc
	global_store_dwordx2 v[112:113], v[110:111], off offset:2048
	v_cvt_pk_bf16_f32 v106, v106, v107
	s_waitcnt lgkmcnt(0)
	v_add_f32_e32 v114, v114, v115
	s_nop 1
	v_mov_b32_dpp v115, v114 row_half_mirror row_mask:0xf bank_mask:0xf bound_ctrl:1
	v_cvt_pk_bf16_f32 v107, v108, v109
	global_store_dwordx2 v[112:113], v[106:107], off offset:2560
	v_cvt_pk_bf16_f32 v106, v98, v99
	v_cvt_pk_bf16_f32 v107, v100, v101
	s_waitcnt lgkmcnt(0)
	v_add_f32_e32 v114, v114, v115
	s_nop 1
	v_mov_b32_dpp v115, v114 row_mirror row_mask:0xf bank_mask:0xf bound_ctrl:1
	global_store_dwordx2 v[112:113], v[106:107], off offset:3072
	v_cvt_pk_bf16_f32 v100, v102, v103
	v_cvt_pk_bf16_f32 v101, v104, v105
	global_store_dwordx2 v[112:113], v[100:101], off offset:3584
	s_waitcnt lgkmcnt(0)
	v_add_f32_e32 v110, v114, v115
	v_mov_b32_e32 v111, v110
	v_mov_b32_e32 v207, v110
	s_nop 1
	v_permlane16_swap_b32_e32 v207, v111
	s_waitcnt lgkmcnt(0)
	v_add_f32_e32 v98, v207, v111
	v_mov_b32_e32 v99, v98
	v_mov_b32_e32 v207, v98
	s_nop 1
	v_permlane32_swap_b32_e32 v207, v99
	s_and_saveexec_b64 s[26:27], s[4:5]
	s_cbranch_execz .LBB0_74
	s_waitcnt lgkmcnt(0)
	v_add_f32_e32 v98, v207, v99
	v_fmamk_f32 v98, v98, 0x3a800000, v193
	v_mul_f32_e32 v99, 0x4f800000, v98
	v_cmp_gt_f32_e32 vcc, s53, v98
	s_nop 1
	v_cndmask_b32_e32 v98, v98, v99, vcc
	v_sqrt_f32_e32 v99, v98
	s_nop 0
	v_add_u32_e32 v100, -1, v99
	v_fma_f32 v102, -v100, v99, v98
	v_add_u32_e32 v101, 1, v99
	v_cmp_ge_f32_e64 s[6:7], 0, v102
	s_nop 1
	v_cndmask_b32_e64 v100, v99, v100, s[6:7]
	v_fma_f32 v99, -v101, v99, v98
	v_cmp_lt_f32_e64 s[6:7], 0, v99
	s_nop 1
	v_cndmask_b32_e64 v99, v100, v101, s[6:7]
	v_mul_f32_e32 v100, 0x37800000, v99
	v_cndmask_b32_e32 v99, v99, v100, vcc
	v_cmp_class_f32_e32 vcc, v98, v194
	s_nop 1
	v_cndmask_b32_e32 v98, v99, v98, vcc
	v_div_scale_f32 v99, s[6:7], v98, v98, 1.0
	v_rcp_f32_e32 v100, v99
	s_add_u32 s6, s38, s18
	s_addc_u32 s7, s39, s19
	v_fma_f32 v101, -v99, v100, 1.0
	v_fmac_f32_e32 v100, v101, v100
	v_div_scale_f32 v101, vcc, 1.0, v98, 1.0
	v_mul_f32_e32 v102, v101, v100
	v_fma_f32 v103, -v99, v102, v101
	v_fmac_f32_e32 v102, v103, v100
	v_fma_f32 v99, -v99, v102, v101
	v_div_fmas_f32 v99, v99, v100, v102
	v_div_fixup_f32 v98, v99, v98, 1.0
	global_store_dword v195, v98, s[6:7] offset:8
.LBB0_74:
	s_or_b64 exec, exec, s[26:27]
	v_mul_f32_e32 v98, v79, v79
	s_waitcnt lgkmcnt(0)
	v_mul_f32_e32 v99, v81, v81
	v_fmac_f32_e32 v98, v78, v78
	v_fmac_f32_e32 v99, v80, v80
	v_add_f32_e32 v98, v98, v99
	v_mul_f32_e32 v99, v75, v75
	v_mul_f32_e32 v100, v77, v77
	v_fmac_f32_e32 v99, v74, v74
	v_fmac_f32_e32 v100, v76, v76
	v_add_f32_e32 v99, v99, v100
	v_add_f32_e32 v98, v98, v99
	v_mul_f32_e32 v99, v71, v71
	v_mul_f32_e32 v100, v73, v73
	v_fmac_f32_e32 v99, v70, v70
	v_fmac_f32_e32 v100, v72, v72
	v_add_f32_e32 v99, v99, v100
	v_add_f32_e32 v98, v98, v99
	v_mul_f32_e32 v99, v67, v67
	v_mul_f32_e32 v100, v69, v69
	v_fmac_f32_e32 v99, v66, v66
	v_fmac_f32_e32 v100, v68, v68
	v_add_f32_e32 v99, v99, v100
	v_add_f32_e32 v98, v98, v99
	s_nop 1
	v_mov_b32_dpp v99, v98 quad_perm:[1,0,3,2] row_mask:0xf bank_mask:0xf bound_ctrl:1
	v_cvt_pk_bf16_f32 v90, v90, v91
	v_cvt_pk_bf16_f32 v91, v92, v93
	v_add_co_u32_e32 v92, vcc, 0x4001000, v130
	s_waitcnt lgkmcnt(0)
	v_add_f32_e32 v98, v98, v99
	s_nop 1
	v_mov_b32_dpp v99, v98 quad_perm:[2,3,0,1] row_mask:0xf bank_mask:0xf bound_ctrl:1
	v_addc_co_u32_e32 v93, vcc, 0, v131, vcc
	global_store_dwordx2 v[92:93], v[90:91], off
	v_cvt_pk_bf16_f32 v86, v86, v87
	s_waitcnt lgkmcnt(0)
	v_add_f32_e32 v98, v98, v99
	s_nop 1
	v_mov_b32_dpp v99, v98 row_half_mirror row_mask:0xf bank_mask:0xf bound_ctrl:1
	v_cvt_pk_bf16_f32 v87, v88, v89
	global_store_dwordx2 v[92:93], v[86:87], off offset:512
	v_cvt_pk_bf16_f32 v86, v82, v83
	v_cvt_pk_bf16_f32 v87, v84, v85
	s_waitcnt lgkmcnt(0)
	v_add_f32_e32 v98, v98, v99
	s_nop 1
	v_mov_b32_dpp v99, v98 row_mirror row_mask:0xf bank_mask:0xf bound_ctrl:1
	global_store_dwordx2 v[92:93], v[86:87], off offset:1024
	v_cvt_pk_bf16_f32 v84, v94, v95
	v_cvt_pk_bf16_f32 v85, v96, v97
	global_store_dwordx2 v[92:93], v[84:85], off offset:1536
	s_waitcnt lgkmcnt(0)
	v_add_f32_e32 v90, v98, v99
	v_mov_b32_e32 v91, v90
	v_mov_b32_e32 v207, v90
	s_nop 1
	v_permlane16_swap_b32_e32 v207, v91
	s_waitcnt lgkmcnt(0)
	v_add_f32_e32 v82, v207, v91
	v_mov_b32_e32 v83, v82
	v_mov_b32_e32 v207, v82
	s_nop 1
	v_permlane32_swap_b32_e32 v207, v83
	s_and_saveexec_b64 s[26:27], s[4:5]
	s_cbranch_execz .LBB0_76
	s_waitcnt lgkmcnt(0)
	v_add_f32_e32 v82, v207, v83
	v_fmamk_f32 v82, v82, 0x3a800000, v193
	v_mul_f32_e32 v83, 0x4f800000, v82
	v_cmp_gt_f32_e32 vcc, s53, v82
	s_nop 1
	v_cndmask_b32_e32 v82, v82, v83, vcc
	v_sqrt_f32_e32 v83, v82
	s_nop 0
	v_add_u32_e32 v84, -1, v83
	v_fma_f32 v86, -v84, v83, v82
	v_add_u32_e32 v85, 1, v83
	v_cmp_ge_f32_e64 s[6:7], 0, v86
	s_nop 1
	v_cndmask_b32_e64 v84, v83, v84, s[6:7]
	v_fma_f32 v83, -v85, v83, v82
	v_cmp_lt_f32_e64 s[6:7], 0, v83
	s_nop 1
	v_cndmask_b32_e64 v83, v84, v85, s[6:7]
	v_mul_f32_e32 v84, 0x37800000, v83
	v_cndmask_b32_e32 v83, v83, v84, vcc
	v_cmp_class_f32_e32 vcc, v82, v194
	s_nop 1
	v_cndmask_b32_e32 v82, v83, v82, vcc
	v_div_scale_f32 v83, s[6:7], v82, v82, 1.0
	v_rcp_f32_e32 v84, v83
	s_add_u32 s6, s38, s18
	s_addc_u32 s7, s39, s19
	v_fma_f32 v85, -v83, v84, 1.0
	v_fmac_f32_e32 v84, v85, v84
	v_div_scale_f32 v85, vcc, 1.0, v82, 1.0
	v_mul_f32_e32 v86, v85, v84
	v_fma_f32 v87, -v83, v86, v85
	v_fmac_f32_e32 v86, v87, v84
	v_fma_f32 v83, -v83, v86, v85
	v_div_fmas_f32 v83, v83, v84, v86
	v_div_fixup_f32 v82, v83, v82, 1.0
	global_store_dword v195, v82, s[6:7] offset:12
.LBB0_76:
	s_or_b64 exec, exec, s[26:27]
	v_mul_f32_e32 v82, v63, v63
	s_waitcnt lgkmcnt(0)
	v_mul_f32_e32 v83, v65, v65
	v_fmac_f32_e32 v82, v62, v62
	v_fmac_f32_e32 v83, v64, v64
	v_add_f32_e32 v82, v82, v83
	v_mul_f32_e32 v83, v59, v59
	v_mul_f32_e32 v84, v61, v61
	v_fmac_f32_e32 v83, v58, v58
	v_fmac_f32_e32 v84, v60, v60
	v_add_f32_e32 v83, v83, v84
	v_add_f32_e32 v82, v82, v83
	v_mul_f32_e32 v83, v55, v55
	v_mul_f32_e32 v84, v57, v57
	v_fmac_f32_e32 v83, v54, v54
	v_fmac_f32_e32 v84, v56, v56
	v_add_f32_e32 v83, v83, v84
	v_add_f32_e32 v82, v82, v83
	v_mul_f32_e32 v83, v51, v51
	v_mul_f32_e32 v84, v53, v53
	v_fmac_f32_e32 v83, v50, v50
	v_fmac_f32_e32 v84, v52, v52
	v_add_f32_e32 v83, v83, v84
	v_add_f32_e32 v82, v82, v83
	s_nop 1
	v_mov_b32_dpp v83, v82 quad_perm:[1,0,3,2] row_mask:0xf bank_mask:0xf bound_ctrl:1
	v_cvt_pk_bf16_f32 v78, v78, v79
	v_cvt_pk_bf16_f32 v79, v80, v81
	v_add_co_u32_e32 v80, vcc, 0x4001000, v130
	s_waitcnt lgkmcnt(0)
	v_add_f32_e32 v82, v82, v83
	s_nop 1
	v_mov_b32_dpp v83, v82 quad_perm:[2,3,0,1] row_mask:0xf bank_mask:0xf bound_ctrl:1
	v_addc_co_u32_e32 v81, vcc, 0, v131, vcc
	global_store_dwordx2 v[80:81], v[78:79], off offset:2048
	v_cvt_pk_bf16_f32 v74, v74, v75
	s_waitcnt lgkmcnt(0)
	v_add_f32_e32 v82, v82, v83
	s_nop 1
	v_mov_b32_dpp v83, v82 row_half_mirror row_mask:0xf bank_mask:0xf bound_ctrl:1
	v_cvt_pk_bf16_f32 v75, v76, v77
	global_store_dwordx2 v[80:81], v[74:75], off offset:2560
	v_cvt_pk_bf16_f32 v74, v70, v71
	v_cvt_pk_bf16_f32 v75, v72, v73
	s_waitcnt lgkmcnt(0)
	v_add_f32_e32 v82, v82, v83
	s_nop 1
	v_mov_b32_dpp v83, v82 row_mirror row_mask:0xf bank_mask:0xf bound_ctrl:1
	global_store_dwordx2 v[80:81], v[74:75], off offset:3072
	v_cvt_pk_bf16_f32 v66, v66, v67
	v_cvt_pk_bf16_f32 v67, v68, v69
	global_store_dwordx2 v[80:81], v[66:67], off offset:3584
	s_waitcnt lgkmcnt(0)
	v_add_f32_e32 v78, v82, v83
	v_mov_b32_e32 v79, v78
	v_mov_b32_e32 v207, v78
	s_nop 1
	v_permlane16_swap_b32_e32 v207, v79
	s_waitcnt lgkmcnt(0)
	v_add_f32_e32 v70, v207, v79
	v_mov_b32_e32 v71, v70
	v_mov_b32_e32 v207, v70
	s_nop 1
	v_permlane32_swap_b32_e32 v207, v71
	s_and_saveexec_b64 s[26:27], s[4:5]
	s_cbranch_execz .LBB0_78
	s_waitcnt lgkmcnt(0)
	v_add_f32_e32 v66, v207, v71
	v_fmamk_f32 v66, v66, 0x3a800000, v193
	v_mul_f32_e32 v67, 0x4f800000, v66
	v_cmp_gt_f32_e32 vcc, s53, v66
	s_nop 1
	v_cndmask_b32_e32 v66, v66, v67, vcc
	v_sqrt_f32_e32 v67, v66
	s_nop 0
	v_add_u32_e32 v68, -1, v67
	v_fma_f32 v70, -v68, v67, v66
	v_add_u32_e32 v69, 1, v67
	v_cmp_ge_f32_e64 s[6:7], 0, v70
	s_nop 1
	v_cndmask_b32_e64 v68, v67, v68, s[6:7]
	v_fma_f32 v67, -v69, v67, v66
	v_cmp_lt_f32_e64 s[6:7], 0, v67
	s_nop 1
	v_cndmask_b32_e64 v67, v68, v69, s[6:7]
	v_mul_f32_e32 v68, 0x37800000, v67
	v_cndmask_b32_e32 v67, v67, v68, vcc
	v_cmp_class_f32_e32 vcc, v66, v194
	s_nop 1
	v_cndmask_b32_e32 v66, v67, v66, vcc
	v_div_scale_f32 v67, s[6:7], v66, v66, 1.0
	v_rcp_f32_e32 v68, v67
	s_add_u32 s6, s38, s18
	s_addc_u32 s7, s39, s19
	v_fma_f32 v69, -v67, v68, 1.0
	v_fmac_f32_e32 v68, v69, v68
	v_div_scale_f32 v69, vcc, 1.0, v66, 1.0
	v_mul_f32_e32 v70, v69, v68
	v_fma_f32 v71, -v67, v70, v69
	v_fmac_f32_e32 v70, v71, v68
	v_fma_f32 v67, -v67, v70, v69
	v_div_fmas_f32 v67, v67, v68, v70
	v_div_fixup_f32 v66, v67, v66, 1.0
	global_store_dword v195, v66, s[6:7] offset:16
.LBB0_78:
	s_or_b64 exec, exec, s[26:27]
	v_mul_f32_e32 v66, v47, v47
	v_mul_f32_e32 v67, v49, v49
	v_fmac_f32_e32 v66, v46, v46
	v_fmac_f32_e32 v67, v48, v48
	v_add_f32_e32 v66, v66, v67
	v_mul_f32_e32 v67, v43, v43
	v_mul_f32_e32 v68, v45, v45
	v_fmac_f32_e32 v67, v42, v42
	v_fmac_f32_e32 v68, v44, v44
	v_add_f32_e32 v67, v67, v68
	v_add_f32_e32 v66, v66, v67
	v_mul_f32_e32 v67, v39, v39
	v_mul_f32_e32 v68, v41, v41
	v_fmac_f32_e32 v67, v38, v38
	v_fmac_f32_e32 v68, v40, v40
	v_add_f32_e32 v67, v67, v68
	v_add_f32_e32 v66, v66, v67
	v_mul_f32_e32 v67, v35, v35
	v_mul_f32_e32 v68, v37, v37
	v_fmac_f32_e32 v67, v34, v34
	v_fmac_f32_e32 v68, v36, v36
	v_add_f32_e32 v67, v67, v68
	v_add_f32_e32 v66, v66, v67
	s_nop 1
	v_mov_b32_dpp v67, v66 quad_perm:[1,0,3,2] row_mask:0xf bank_mask:0xf bound_ctrl:1
	v_cvt_pk_bf16_f32 v62, v62, v63
	v_cvt_pk_bf16_f32 v63, v64, v65
	v_add_co_u32_e32 v64, vcc, 0x4002000, v130
	s_waitcnt lgkmcnt(0)
	v_add_f32_e32 v66, v66, v67
	s_nop 1
	v_mov_b32_dpp v67, v66 quad_perm:[2,3,0,1] row_mask:0xf bank_mask:0xf bound_ctrl:1
	v_addc_co_u32_e32 v65, vcc, 0, v131, vcc
	global_store_dwordx2 v[64:65], v[62:63], off
	v_cvt_pk_bf16_f32 v58, v58, v59
	s_waitcnt lgkmcnt(0)
	v_add_f32_e32 v66, v66, v67
	s_nop 1
	v_mov_b32_dpp v67, v66 row_half_mirror row_mask:0xf bank_mask:0xf bound_ctrl:1
	v_cvt_pk_bf16_f32 v59, v60, v61
	global_store_dwordx2 v[64:65], v[58:59], off offset:512
	v_cvt_pk_bf16_f32 v58, v54, v55
	v_cvt_pk_bf16_f32 v59, v56, v57
	s_waitcnt lgkmcnt(0)
	v_add_f32_e32 v66, v66, v67
	s_nop 1
	v_mov_b32_dpp v67, v66 row_mirror row_mask:0xf bank_mask:0xf bound_ctrl:1
	global_store_dwordx2 v[64:65], v[58:59], off offset:1024
	v_cvt_pk_bf16_f32 v50, v50, v51
	v_cvt_pk_bf16_f32 v51, v52, v53
	global_store_dwordx2 v[64:65], v[50:51], off offset:1536
	s_waitcnt lgkmcnt(0)
	v_add_f32_e32 v62, v66, v67
	v_mov_b32_e32 v63, v62
	v_mov_b32_e32 v207, v62
	s_nop 1
	v_permlane16_swap_b32_e32 v207, v63
	s_waitcnt lgkmcnt(0)
	v_add_f32_e32 v54, v207, v63
	v_mov_b32_e32 v55, v54
	v_mov_b32_e32 v207, v54
	s_nop 1
	v_permlane32_swap_b32_e32 v207, v55
	s_and_saveexec_b64 s[26:27], s[4:5]
	s_cbranch_execz .LBB0_80
	s_waitcnt lgkmcnt(0)
	v_add_f32_e32 v50, v207, v55
	v_fmamk_f32 v50, v50, 0x3a800000, v193
	v_mul_f32_e32 v51, 0x4f800000, v50
	v_cmp_gt_f32_e32 vcc, s53, v50
	s_nop 1
	v_cndmask_b32_e32 v50, v50, v51, vcc
	v_sqrt_f32_e32 v51, v50
	s_nop 0
	v_add_u32_e32 v52, -1, v51
	v_fma_f32 v54, -v52, v51, v50
	v_add_u32_e32 v53, 1, v51
	v_cmp_ge_f32_e64 s[6:7], 0, v54
	s_nop 1
	v_cndmask_b32_e64 v52, v51, v52, s[6:7]
	v_fma_f32 v51, -v53, v51, v50
	v_cmp_lt_f32_e64 s[6:7], 0, v51
	s_nop 1
	v_cndmask_b32_e64 v51, v52, v53, s[6:7]
	v_mul_f32_e32 v52, 0x37800000, v51
	v_cndmask_b32_e32 v51, v51, v52, vcc
	v_cmp_class_f32_e32 vcc, v50, v194
	s_nop 1
	v_cndmask_b32_e32 v50, v51, v50, vcc
	v_div_scale_f32 v51, s[6:7], v50, v50, 1.0
	v_rcp_f32_e32 v52, v51
	s_add_u32 s6, s38, s18
	s_addc_u32 s7, s39, s19
	v_fma_f32 v53, -v51, v52, 1.0
	v_fmac_f32_e32 v52, v53, v52
	v_div_scale_f32 v53, vcc, 1.0, v50, 1.0
	v_mul_f32_e32 v54, v53, v52
	v_fma_f32 v55, -v51, v54, v53
	v_fmac_f32_e32 v54, v55, v52
	v_fma_f32 v51, -v51, v54, v53
	v_div_fmas_f32 v51, v51, v52, v54
	v_div_fixup_f32 v50, v51, v50, 1.0
	global_store_dword v195, v50, s[6:7] offset:20
.LBB0_80:
	s_or_b64 exec, exec, s[26:27]
	v_mul_f32_e32 v50, v31, v31
	v_mul_f32_e32 v51, v33, v33
	v_fmac_f32_e32 v50, v30, v30
	v_fmac_f32_e32 v51, v32, v32
	v_add_f32_e32 v50, v50, v51
	v_mul_f32_e32 v51, v27, v27
	v_mul_f32_e32 v52, v29, v29
	v_fmac_f32_e32 v51, v26, v26
	v_fmac_f32_e32 v52, v28, v28
	v_add_f32_e32 v51, v51, v52
	v_add_f32_e32 v50, v50, v51
	v_mul_f32_e32 v51, v23, v23
	v_mul_f32_e32 v52, v25, v25
	v_fmac_f32_e32 v51, v22, v22
	v_fmac_f32_e32 v52, v24, v24
	v_add_f32_e32 v51, v51, v52
	v_add_f32_e32 v50, v50, v51
	v_mul_f32_e32 v51, v19, v19
	v_mul_f32_e32 v52, v21, v21
	v_fmac_f32_e32 v51, v18, v18
	v_fmac_f32_e32 v52, v20, v20
	v_add_f32_e32 v51, v51, v52
	v_add_f32_e32 v50, v50, v51
	s_nop 1
	v_mov_b32_dpp v51, v50 quad_perm:[1,0,3,2] row_mask:0xf bank_mask:0xf bound_ctrl:1
	v_cvt_pk_bf16_f32 v46, v46, v47
	v_cvt_pk_bf16_f32 v47, v48, v49
	v_add_co_u32_e32 v48, vcc, 0x4002000, v130
	s_waitcnt lgkmcnt(0)
	v_add_f32_e32 v50, v50, v51
	s_nop 1
	v_mov_b32_dpp v51, v50 quad_perm:[2,3,0,1] row_mask:0xf bank_mask:0xf bound_ctrl:1
	v_addc_co_u32_e32 v49, vcc, 0, v131, vcc
	global_store_dwordx2 v[48:49], v[46:47], off offset:2048
	v_cvt_pk_bf16_f32 v42, v42, v43
	s_waitcnt lgkmcnt(0)
	v_add_f32_e32 v50, v50, v51
	s_nop 1
	v_mov_b32_dpp v51, v50 row_half_mirror row_mask:0xf bank_mask:0xf bound_ctrl:1
	v_cvt_pk_bf16_f32 v43, v44, v45
	global_store_dwordx2 v[48:49], v[42:43], off offset:2560
	v_cvt_pk_bf16_f32 v42, v38, v39
	v_cvt_pk_bf16_f32 v43, v40, v41
	s_waitcnt lgkmcnt(0)
	v_add_f32_e32 v50, v50, v51
	s_nop 1
	v_mov_b32_dpp v51, v50 row_mirror row_mask:0xf bank_mask:0xf bound_ctrl:1
	global_store_dwordx2 v[48:49], v[42:43], off offset:3072
	v_cvt_pk_bf16_f32 v34, v34, v35
	v_cvt_pk_bf16_f32 v35, v36, v37
	global_store_dwordx2 v[48:49], v[34:35], off offset:3584
	s_waitcnt lgkmcnt(0)
	v_add_f32_e32 v46, v50, v51
	v_mov_b32_e32 v47, v46
	v_mov_b32_e32 v207, v46
	s_nop 1
	v_permlane16_swap_b32_e32 v207, v47
	s_waitcnt lgkmcnt(0)
	v_add_f32_e32 v38, v207, v47
	v_mov_b32_e32 v39, v38
	v_mov_b32_e32 v207, v38
	s_nop 1
	v_permlane32_swap_b32_e32 v207, v39
	s_and_saveexec_b64 s[26:27], s[4:5]
	s_cbranch_execz .LBB0_82
	s_waitcnt lgkmcnt(0)
	v_add_f32_e32 v34, v207, v39
	v_fmamk_f32 v34, v34, 0x3a800000, v193
	v_mul_f32_e32 v35, 0x4f800000, v34
	v_cmp_gt_f32_e32 vcc, s53, v34
	s_nop 1
	v_cndmask_b32_e32 v34, v34, v35, vcc
	v_sqrt_f32_e32 v35, v34
	s_nop 0
	v_add_u32_e32 v36, -1, v35
	v_fma_f32 v38, -v36, v35, v34
	v_add_u32_e32 v37, 1, v35
	v_cmp_ge_f32_e64 s[6:7], 0, v38
	s_nop 1
	v_cndmask_b32_e64 v36, v35, v36, s[6:7]
	v_fma_f32 v35, -v37, v35, v34
	v_cmp_lt_f32_e64 s[6:7], 0, v35
	s_nop 1
	v_cndmask_b32_e64 v35, v36, v37, s[6:7]
	v_mul_f32_e32 v36, 0x37800000, v35
	v_cndmask_b32_e32 v35, v35, v36, vcc
	v_cmp_class_f32_e32 vcc, v34, v194
	s_nop 1
	v_cndmask_b32_e32 v34, v35, v34, vcc
	v_div_scale_f32 v35, s[6:7], v34, v34, 1.0
	v_rcp_f32_e32 v36, v35
	s_add_u32 s6, s38, s18
	s_addc_u32 s7, s39, s19
	v_fma_f32 v37, -v35, v36, 1.0
	v_fmac_f32_e32 v36, v37, v36
	v_div_scale_f32 v37, vcc, 1.0, v34, 1.0
	v_mul_f32_e32 v38, v37, v36
	v_fma_f32 v39, -v35, v38, v37
	v_fmac_f32_e32 v38, v39, v36
	v_fma_f32 v35, -v35, v38, v37
	v_div_fmas_f32 v35, v35, v36, v38
	v_div_fixup_f32 v34, v35, v34, 1.0
	global_store_dword v195, v34, s[6:7] offset:24
.LBB0_82:
	s_or_b64 exec, exec, s[26:27]
	v_mul_f32_e32 v34, v15, v15
	v_mul_f32_e32 v35, v17, v17
	v_fmac_f32_e32 v34, v14, v14
	v_fmac_f32_e32 v35, v16, v16
	v_add_f32_e32 v34, v34, v35
	v_mul_f32_e32 v35, v11, v11
	v_mul_f32_e32 v36, v13, v13
	v_fmac_f32_e32 v35, v10, v10
	v_fmac_f32_e32 v36, v12, v12
	v_add_f32_e32 v35, v35, v36
	v_add_f32_e32 v34, v34, v35
	v_mul_f32_e32 v35, v7, v7
	v_mul_f32_e32 v36, v9, v9
	v_fmac_f32_e32 v35, v6, v6
	v_fmac_f32_e32 v36, v8, v8
	v_add_f32_e32 v35, v35, v36
	v_add_f32_e32 v34, v34, v35
	s_waitcnt vmcnt(24)
	v_mul_f32_e32 v35, v3, v3
	v_mul_f32_e32 v36, v5, v5
	v_fmac_f32_e32 v35, v2, v2
	v_fmac_f32_e32 v36, v4, v4
	v_add_f32_e32 v35, v35, v36
	v_add_f32_e32 v34, v34, v35
	s_nop 1
	v_mov_b32_dpp v35, v34 quad_perm:[1,0,3,2] row_mask:0xf bank_mask:0xf bound_ctrl:1
	v_cvt_pk_bf16_f32 v30, v30, v31
	v_cvt_pk_bf16_f32 v31, v32, v33
	v_add_co_u32_e32 v32, vcc, 0x4003000, v130
	s_waitcnt lgkmcnt(0)
	v_add_f32_e32 v34, v34, v35
	s_nop 1
	v_mov_b32_dpp v35, v34 quad_perm:[2,3,0,1] row_mask:0xf bank_mask:0xf bound_ctrl:1
	v_addc_co_u32_e32 v33, vcc, 0, v131, vcc
	global_store_dwordx2 v[32:33], v[30:31], off
	v_cvt_pk_bf16_f32 v26, v26, v27
	s_waitcnt lgkmcnt(0)
	v_add_f32_e32 v34, v34, v35
	s_nop 1
	v_mov_b32_dpp v35, v34 row_half_mirror row_mask:0xf bank_mask:0xf bound_ctrl:1
	v_cvt_pk_bf16_f32 v27, v28, v29
	global_store_dwordx2 v[32:33], v[26:27], off offset:512
	v_cvt_pk_bf16_f32 v26, v22, v23
	v_cvt_pk_bf16_f32 v27, v24, v25
	s_waitcnt lgkmcnt(0)
	v_add_f32_e32 v34, v34, v35
	s_nop 1
	v_mov_b32_dpp v35, v34 row_mirror row_mask:0xf bank_mask:0xf bound_ctrl:1
	global_store_dwordx2 v[32:33], v[26:27], off offset:1024
	v_cvt_pk_bf16_f32 v18, v18, v19
	v_cvt_pk_bf16_f32 v19, v20, v21
	global_store_dwordx2 v[32:33], v[18:19], off offset:1536
	s_waitcnt lgkmcnt(0)
	v_add_f32_e32 v30, v34, v35
	v_mov_b32_e32 v31, v30
	v_mov_b32_e32 v207, v30
	s_nop 1
	v_permlane16_swap_b32_e32 v207, v31
	s_waitcnt lgkmcnt(0)
	v_add_f32_e32 v22, v207, v31
	v_mov_b32_e32 v23, v22
	v_mov_b32_e32 v207, v22
	s_nop 1
	v_permlane32_swap_b32_e32 v207, v23
	s_and_saveexec_b64 s[26:27], s[4:5]
	s_cbranch_execz .LBB0_11
	s_waitcnt lgkmcnt(0)
	v_add_f32_e32 v18, v207, v23
	v_fmamk_f32 v18, v18, 0x3a800000, v193
	v_mul_f32_e32 v19, 0x4f800000, v18
	v_cmp_gt_f32_e32 vcc, s53, v18
	s_nop 1
	v_cndmask_b32_e32 v18, v18, v19, vcc
	v_sqrt_f32_e32 v19, v18
	s_nop 0
	v_add_u32_e32 v20, -1, v19
	v_fma_f32 v22, -v20, v19, v18
	v_add_u32_e32 v21, 1, v19
	v_cmp_ge_f32_e64 s[6:7], 0, v22
	s_nop 1
	v_cndmask_b32_e64 v20, v19, v20, s[6:7]
	v_fma_f32 v19, -v21, v19, v18
	v_cmp_lt_f32_e64 s[6:7], 0, v19
	s_nop 1
	v_cndmask_b32_e64 v19, v20, v21, s[6:7]
	v_mul_f32_e32 v20, 0x37800000, v19
	v_cndmask_b32_e32 v19, v19, v20, vcc
	v_cmp_class_f32_e32 vcc, v18, v194
	s_nop 1
	v_cndmask_b32_e32 v18, v19, v18, vcc
	v_div_scale_f32 v19, s[6:7], v18, v18, 1.0
	v_rcp_f32_e32 v20, v19
	s_add_u32 s6, s38, s18
	s_addc_u32 s7, s39, s19
	v_fma_f32 v21, -v19, v20, 1.0
	v_fmac_f32_e32 v20, v21, v20
	v_div_scale_f32 v21, vcc, 1.0, v18, 1.0
	v_mul_f32_e32 v22, v21, v20
	v_fma_f32 v23, -v19, v22, v21
	v_fmac_f32_e32 v22, v23, v20
	v_fma_f32 v19, -v19, v22, v21
	v_div_fmas_f32 v19, v19, v20, v22
	v_div_fixup_f32 v18, v19, v18, 1.0
	global_store_dword v195, v18, s[6:7] offset:28
	s_branch .LBB0_11
